# MIX stores (scan finisher, attention group epilogue) nt
# baseline (speedup 1.0000x reference)
; #define LAS __attribute__((address_space(3)))
; __device__ __forceinline__ unsigned pk2(float lo, float hi) { return pg8::cvt_pk_bf16_v(lo, hi); }
; __device__ __forceinline__ float siluf(float x) { return x * __builtin_amdgcn_rcpf(1.0f + __expf(-x)); }
; __device__ __forceinline__ void unpack8(v4u w, float (&f)[8]) { f[0] = bflo(w.x); f[1] = bfhi(w.x); f[2] = bflo(w.y); f[3] = bfhi(w.y); f[4] = bflo(w.z); f[5] = bfhi(w.z); f[6] = bflo(w.w); f[7] = bfhi(w.w); }
; __device__ __forceinline__ void scan_prompt_wg(const Params& P, LAS unsigned char* lds, int s, int h, int wave, int lane) {
;     ...
;                 const LAS unsigned char* ot = lds + (((n - 1) & 1) ? OT_B : OT_A) + ft * 128 + fp * 32;
;                 const LAS unsigned char* zt = lds + ZT_OFF + ((n - 1) & 1) * 8192 + ft * 128 + fp * 32;
;                 float o[16], zf[16]; { float t0[8], t1[8]; unpack8(*(const LAS v4u*)ot, t0); unpack8(*(const LAS v4u*)(ot + 16), t1);
; #pragma unroll
;                     for (int i = 0; i < 8; ++i) { o[i] = t0[i]; o[8 + i] = t1[i]; }
;                     unpack8(*(const LAS v4u*)zt, t0); unpack8(*(const LAS v4u*)(zt + 16), t1);
; #pragma unroll
;                     for (int i = 0; i < 8; ++i) { zf[i] = t0[i]; zf[8 + i] = t1[i]; } }
;                 float ss = 0.f;
; #pragma unroll
;                 for (int i = 0; i < 16; ++i) ss += o[i] * o[i];
;                 ss += __shfl_xor(ss, 1); ss += __shfl_xor(ss, 2);
;                 const float rstd = __builtin_amdgcn_rsqf(ss * (1.0f / 64.0f) + 1e-6f);
;                 float r[16];
; #pragma unroll
;                 for (int i = 0; i < 16; ++i) r[i] = o[i] * rstd * gg[i] * siluf(zf[i]);
;                 bf16* mp = Mr + (size_t)(n - 1) * 64 * 1024;
;                 v4u w0, w1; w0.x = pk2(r[0], r[1]); w0.y = pk2(r[2], r[3]); w0.z = pk2(r[4], r[5]); w0.w = pk2(r[6], r[7]); w1.x = pk2(r[8], r[9]); w1.y = pk2(r[10], r[11]); w1.z = pk2(r[12], r[13]); w1.w = pk2(r[14], r[15]);
;                 *(v4u*)mp = w0; *(v4u*)(mp + 8) = w1;
.LBB0_666:
	v_add_co_u32_e64 v25, s[38:39], s10, 1
	s_nop 0
	v_readfirstlane_b32 s45, v25
	s_and_b64 vcc, exec, s[38:39]
	s_cbranch_vccnz .LBB0_668
	s_and_b32 s20, s10, 1
	v_lshl_add_u32 v25, s20, 13, v27
	ds_read_b128 v[28:31], v25 offset:16
	s_cmp_eq_u32 s20, 0
	s_cselect_b32 s20, s44, 0x20200
	v_add_u32_e32 v32, s20, v26
	ds_read_b128 v[36:39], v32 offset:16
	s_waitcnt lgkmcnt(1)
	v_lshlrev_b32_e32 v34, 16, v31
	v_mul_f32_e32 v33, 0xbfb8aa3b, v34
	v_exp_f32_e32 v48, v33
	ds_read_b128 v[40:43], v25
	ds_read_b128 v[44:47], v32
	v_lshlrev_b32_e32 v62, 16, v29
	s_waitcnt lgkmcnt(2)
	v_lshlrev_b32_e32 v49, 16, v38
	v_add_f32_e32 v25, 1.0, v48
	v_rcp_f32_e32 v25, v25
	v_and_b32_e32 v48, 0xffff0000, v38
	v_and_b32_e32 v63, 0xffff0000, v29
	v_mul_f32_e32 v29, 0xbfb8aa3b, v63
	v_mul_f32_e32 v38, v25, v34
	v_mul_f32_e32 v25, 0xbfb8aa3b, v62
	v_exp_f32_e32 v25, v25
	v_exp_f32_e32 v29, v29
	v_lshlrev_b32_e32 v68, 16, v37
	v_and_b32_e32 v69, 0xffff0000, v37
	v_add_f32_e32 v25, 1.0, v25
	v_rcp_f32_e32 v66, v25
	v_add_f32_e32 v25, 1.0, v29
	v_rcp_f32_e32 v67, v25
	v_and_b32_e32 v37, 0xffff0000, v28
	v_and_b32_e32 v60, 0xffff0000, v31
	s_waitcnt lgkmcnt(1)
	v_lshlrev_b32_e32 v74, 16, v43
	v_pk_mul_f32 v[62:63], v[66:67], v[62:63]
	v_lshlrev_b32_e32 v66, 16, v36
	v_and_b32_e32 v67, 0xffff0000, v36
	v_lshlrev_b32_e32 v36, 16, v28
	v_mul_f32_e32 v25, 0xbfb8aa3b, v36
	v_exp_f32_e32 v25, v25
	v_mul_f32_e32 v28, 0xbfb8aa3b, v37
	v_exp_f32_e32 v31, v28
	v_and_b32_e32 v75, 0xffff0000, v43
	v_add_f32_e32 v25, 1.0, v25
	v_rcp_f32_e32 v72, v25
	v_add_f32_e32 v25, 1.0, v31
	v_rcp_f32_e32 v73, v25
	v_mul_f32_e32 v25, 0xbfb8aa3b, v74
	v_exp_f32_e32 v25, v25
	v_mul_f32_e32 v31, 0xbfb8aa3b, v75
	v_exp_f32_e32 v31, v31
	v_pk_mul_f32 v[36:37], v[72:73], v[36:37]
	v_add_f32_e32 v25, 1.0, v25
	v_rcp_f32_e32 v72, v25
	v_add_f32_e32 v25, 1.0, v31
	v_rcp_f32_e32 v73, v25
	s_waitcnt lgkmcnt(0)
	v_lshlrev_b32_e32 v76, 16, v47
	v_and_b32_e32 v77, 0xffff0000, v47
	v_and_b32_e32 v47, 0xffff0000, v42
	v_pk_mul_f32 v[72:73], v[72:73], v[74:75]
	v_lshlrev_b32_e32 v74, 16, v46
	v_and_b32_e32 v75, 0xffff0000, v46
	v_lshlrev_b32_e32 v46, 16, v42
	v_mul_f32_e32 v25, 0xbfb8aa3b, v46
	v_exp_f32_e32 v25, v25
	v_mul_f32_e32 v31, 0xbfb8aa3b, v47
	v_exp_f32_e32 v31, v31
	v_lshlrev_b32_e32 v84, 16, v41
	v_add_f32_e32 v25, 1.0, v25
	v_rcp_f32_e32 v80, v25
	v_add_f32_e32 v25, 1.0, v31
	v_rcp_f32_e32 v81, v25
	v_and_b32_e32 v85, 0xffff0000, v41
	v_mul_f32_e32 v25, 0xbfb8aa3b, v84
	v_exp_f32_e32 v25, v25
	v_mul_f32_e32 v31, 0xbfb8aa3b, v85
	v_exp_f32_e32 v31, v31
	v_lshlrev_b32_e32 v90, 16, v44
	v_add_f32_e32 v25, 1.0, v25
	v_and_b32_e32 v91, 0xffff0000, v44
	v_lshlrev_b32_e32 v82, 16, v45
	v_and_b32_e32 v83, 0xffff0000, v45
	v_rcp_f32_e32 v88, v25
	v_add_f32_e32 v25, 1.0, v31
	v_lshlrev_b32_e32 v44, 16, v40
	v_and_b32_e32 v45, 0xffff0000, v40
	v_pk_mul_f32 v[40:41], v[90:91], v[90:91]
	v_pk_mul_f32 v[86:87], v[82:83], v[82:83]
	v_rcp_f32_e32 v89, v25
	v_add_f32_e32 v25, v40, v41
	v_add_f32_e32 v25, v86, v25
	v_pk_mul_f32 v[42:43], v[74:75], v[74:75]
	v_add_f32_e32 v25, v87, v25
	v_add_f32_e32 v25, v42, v25
	v_pk_mul_f32 v[78:79], v[76:77], v[76:77]
	v_add_f32_e32 v25, v43, v25
	v_add_f32_e32 v25, v78, v25
	v_pk_mul_f32 v[28:29], v[66:67], v[66:67]
	v_add_f32_e32 v25, v79, v25
	v_add_f32_e32 v25, v28, v25
	v_pk_mul_f32 v[70:71], v[68:69], v[68:69]
	v_add_f32_e32 v25, v29, v25
	v_add_f32_e32 v25, v70, v25
	v_pk_mul_f32 v[50:51], v[48:49], v[48:49]
	v_and_b32_e32 v61, 0xffff0000, v39
	v_add_f32_e32 v25, v71, v25
	v_lshlrev_b32_e32 v33, 16, v39
	v_mov_b32_e32 v32, v61
	v_add_f32_e32 v25, v51, v25
	v_pk_mul_f32 v[64:65], v[32:33], v[32:33]
	v_add_f32_e32 v25, v50, v25
	v_add_f32_e32 v25, v65, v25
	v_add_f32_e32 v25, v64, v25
	ds_bpermute_b32 v28, v57, v25
	v_lshlrev_b32_e32 v50, 16, v30
	v_and_b32_e32 v51, 0xffff0000, v30
	v_mul_f32_e32 v29, 0xbfb8aa3b, v44
	v_mul_f32_e32 v31, 0xbfb8aa3b, v45
	s_waitcnt lgkmcnt(0)
	v_add_f32_e32 v25, v25, v28
	ds_bpermute_b32 v32, v58, v25
	v_mul_f32_e32 v30, 0xbfb8aa3b, v51
	v_exp_f32_e32 v29, v29
	v_exp_f32_e32 v31, v31
	v_exp_f32_e32 v34, v30
	s_waitcnt lgkmcnt(0)
	v_add_f32_e32 v25, v25, v32
	v_fmamk_f32 v25, v25, 0x3c800000, v24
	v_rsq_f32_e32 v32, v25
	v_mul_f32_e32 v25, 0xbfb8aa3b, v50
	v_exp_f32_e32 v25, v25
	v_pk_mul_f32 v[40:41], v[80:81], v[46:47]
	v_pk_mul_f32 v[46:47], v[32:33], v[66:67] op_sel_hi:[0,1]
	v_pk_mul_f32 v[46:47], v[10:11], v[46:47]
	v_add_f32_e32 v25, 1.0, v25
	v_pk_mul_f32 v[36:37], v[36:37], v[46:47]
	v_pk_mul_f32 v[46:47], v[32:33], v[68:69] op_sel_hi:[0,1]
	v_add_f32_e32 v28, 1.0, v29
	v_add_f32_e32 v29, 1.0, v31
	v_pk_mul_f32 v[30:31], v[12:13], v[46:47]
	v_rcp_f32_e32 v46, v25
	v_add_f32_e32 v25, 1.0, v34
	v_rcp_f32_e32 v28, v28
	v_rcp_f32_e32 v29, v29
	v_rcp_f32_e32 v47, v25
	v_mul_f32_e32 v25, 0xbfb8aa3b, v60
	v_exp_f32_e32 v25, v25
	v_pk_mul_f32 v[28:29], v[28:29], v[44:45]
	v_pk_mul_f32 v[44:45], v[32:33], v[90:91] op_sel_hi:[0,1]
	v_pk_mul_f32 v[44:45], v[2:3], v[44:45]
	v_add_f32_e32 v25, 1.0, v25
	v_pk_mul_f32 v[28:29], v[28:29], v[44:45]
	v_pk_mul_f32 v[44:45], v[32:33], v[82:83] op_sel_hi:[0,1]
	v_pk_mul_f32 v[62:63], v[62:63], v[30:31]
	v_pk_mul_f32 v[30:31], v[46:47], v[50:51]
	v_pk_mul_f32 v[46:47], v[32:33], v[48:49] op_sel_hi:[0,1]
	v_rcp_f32_e32 v48, v25
	v_pk_mul_f32 v[42:43], v[88:89], v[84:85]
	v_pk_mul_f32 v[44:45], v[4:5], v[44:45]
	v_pk_mul_f32 v[46:47], v[20:21], v[46:47]
	v_pk_mul_f32 v[42:43], v[42:43], v[44:45]
	v_pk_mul_f32 v[44:45], v[32:33], v[74:75] op_sel_hi:[0,1]
	v_pk_mul_f32 v[44:45], v[6:7], v[44:45]
	v_mov_b32_e32 v49, v32
	v_pk_mul_f32 v[40:41], v[40:41], v[44:45]
	v_pk_mul_f32 v[44:45], v[32:33], v[76:77] op_sel_hi:[0,1]
	v_pk_mul_f32 v[46:47], v[30:31], v[46:47] op_sel:[0,1] op_sel_hi:[1,0]
	v_mul_f32_e32 v30, v32, v33
	v_pk_mul_f32 v[32:33], v[48:49], v[60:61]
	v_pk_mul_f32 v[44:45], v[8:9], v[44:45]
	v_mov_b32_e32 v31, v33
	s_lshl_b64 s[20:21], s[10:11], 17
	v_pk_mul_f32 v[44:45], v[72:73], v[44:45]
	v_pk_mul_f32 v[30:31], v[16:17], v[30:31]
	v_mov_b32_e32 v39, v32
	s_cmpk_lg_i32 s10, 0x7f
	v_pk_mul_f32 v[32:33], v[38:39], v[30:31]
	v_lshl_add_u64 v[48:49], v[14:15], 0, s[20:21]
	v_readlane_b32 s96, v247, 24
	v_cvt_pk_bf16_f32 v28, v28, v29
	v_cvt_pk_bf16_f32 v29, v42, v43
	v_cvt_pk_bf16_f32 v30, v40, v41
	v_cvt_pk_bf16_f32 v31, v44, v45
	s_cselect_b64 s[38:39], -1, 0
	v_cvt_pk_bf16_f32 v36, v36, v37
	v_cvt_pk_bf16_f32 v37, v62, v63
	v_cvt_pk_bf16_f32 v38, v46, v47
	v_cvt_pk_bf16_f32 v39, v32, v33
	global_store_dwordx4 v[48:49], v[28:31], off nt
	global_store_dwordx4 v[48:49], v[36:39], off offset:16 nt

; #define LAS __attribute__((address_space(3)))
; __device__ __forceinline__ float siluf(float x) { return x * __builtin_amdgcn_rcpf(1.0f + __expf(-x)); }
; __device__ __forceinline__ void unpack8(v4u w, float (&f)[8]) { f[0] = bflo(w.x); f[1] = bfhi(w.x); f[2] = bflo(w.y); f[3] = bfhi(w.y); f[4] = bflo(w.z); f[5] = bfhi(w.z); f[6] = bflo(w.w); f[7] = bfhi(w.w); }
; __device__ __forceinline__ v4u packf8(const float (&f)[8]) { v4u w; w.x = pk2(f[0], f[1]); w.y = pk2(f[2], f[3]); w.z = pk2(f[4], f[5]); w.w = pk2(f[6], f[7]); return w; }
; __device__ __forceinline__ void attn_group(const Params& P, LAS unsigned char* lds, const LAS float* tabh, int s, int h, int c0, int wave, int lane) {
;     ...
;     {
;         const float l = lsum + __shfl_xor(lsum, 32); const float inv = __builtin_amdgcn_rcpf(l);
;         const size_t mrow0 = (size_t)s * TP + c * 64 + 32 * qb;
;         const bf16* Z = (const bf16*)(P.ws + WS_Z) + mrow0 * 1024 + 512 + h * 64; bf16* MIX = (bf16*)(P.ws + WS_MIX) + mrow0 * 1024 + 512 + h * 64;
;         const int rr = lane >> 3, pc = lane & 7;
;         v4u zb[4];
; #pragma unroll
;         for (int ps = 0; ps < 4; ++ps) zb[ps] = *(const v4u*)(Z + (size_t)(8 * ps + rr) * 1024 + 8 * pc);
;         LAS unsigned char* st = lds + wave * 14336;
; #pragma unroll
;         for (int dt = 0; dt < 2; ++dt)
; #pragma unroll
;             for (int rg = 0; rg < 4; ++rg) { const f32x4 o = {oacc[dt][4 * rg] * inv, oacc[dt][4 * rg + 1] * inv, oacc[dt][4 * rg + 2] * inv, oacc[dt][4 * rg + 3] * inv};
;                 *(LAS f32x4*)(st + l31 * 272 + (32 * dt + 8 * rg + 4 * hh) * 4) = o; }
; #pragma unroll
;         for (int ps = 0; ps < 4; ++ps) { const int row = 8 * ps + rr;
;             const f32x4 a = *(const LAS f32x4*)(st + row * 272 + pc * 32), b = *(const LAS f32x4*)(st + row * 272 + pc * 32 + 16);
;             float z[8]; unpack8(zb[ps], z);
;             float f[8] = {a[0] * siluf(z[0]), a[1] * siluf(z[1]), a[2] * siluf(z[2]), a[3] * siluf(z[3]), b[0] * siluf(z[4]), b[1] * siluf(z[5]), b[2] * siluf(z[6]), b[3] * siluf(z[7])};
;             *(v4u*)(MIX + (size_t)row * 1024 + 8 * pc) = packf8(f); }
.LBB0_743:
	s_lshl_b64 s[38:39], s[10:11], 13
	s_lshl_b32 s10, s43, 6
	s_ashr_i32 s40, s10, 31
	s_add_u32 s38, s38, s10
	s_addc_u32 s39, s39, s40
	s_or_b64 s[38:39], s[38:39], s[16:17]
	s_lshl_b64 s[38:39], s[38:39], 11
	v_readlane_b32 s40, v247, 0
	v_readlane_b32 s41, v247, 1
	s_add_u32 s10, s40, s38
	s_addc_u32 s39, s41, s39
	s_lshl_b32 s38, s42, 7
	s_add_u32 s38, s10, s38
	v_lshlrev_b32_e32 v2, 1, v174
	s_addc_u32 s39, s39, 0
	v_lshlrev_b32_e32 v36, 1, v176
	v_mov_b32_e32 v37, v3
	v_lshl_add_u64 v[46:47], s[38:39], 0, v[2:3]
	v_lshl_add_u64 v[48:49], v[46:47], 0, v[36:37]
	v_add_co_u32_e32 v38, vcc, s78, v48
	ds_bpermute_b32 v2, v1, v118
	s_nop 0
	v_addc_co_u32_e32 v39, vcc, 0, v49, vcc
	global_load_dwordx4 v[38:41], v[38:39], off offset:1024 nt
	v_add_co_u32_e32 v42, vcc, s79, v48
	s_waitcnt lgkmcnt(0)
	v_add_f32_e32 v2, v118, v2
	v_addc_co_u32_e32 v43, vcc, 0, v49, vcc
	global_load_dwordx4 v[42:45], v[42:43], off offset:1024 nt
	v_rcp_f32_e32 v2, v2
	v_mov_b32_e32 v183, v3
	v_mov_b32_e32 v185, v3
	v_pk_mul_f32 v[20:21], v[20:21], v[2:3] op_sel_hi:[1,0]
	v_pk_mul_f32 v[22:23], v[22:23], v[2:3] op_sel_hi:[1,0]
	v_pk_mul_f32 v[4:5], v[4:5], v[2:3] op_sel_hi:[1,0]
	v_pk_mul_f32 v[24:25], v[24:25], v[2:3] op_sel_hi:[1,0]
	v_pk_mul_f32 v[26:27], v[26:27], v[2:3] op_sel_hi:[1,0]
	v_pk_mul_f32 v[28:29], v[28:29], v[2:3] op_sel_hi:[1,0]
	v_pk_mul_f32 v[30:31], v[30:31], v[2:3] op_sel_hi:[1,0]
	v_pk_mul_f32 v[32:33], v[32:33], v[2:3] op_sel_hi:[1,0]
	v_pk_mul_f32 v[34:35], v[34:35], v[2:3] op_sel_hi:[1,0]
	v_pk_mul_f32 v[6:7], v[6:7], v[2:3] op_sel_hi:[1,0]
	v_pk_mul_f32 v[8:9], v[8:9], v[2:3] op_sel_hi:[1,0]
	v_pk_mul_f32 v[10:11], v[10:11], v[2:3] op_sel_hi:[1,0]
	v_pk_mul_f32 v[12:13], v[12:13], v[2:3] op_sel_hi:[1,0]
	v_pk_mul_f32 v[14:15], v[14:15], v[2:3] op_sel_hi:[1,0]
	v_pk_mul_f32 v[16:17], v[16:17], v[2:3] op_sel_hi:[1,0]
	v_pk_mul_f32 v[18:19], v[18:19], v[2:3] op_sel_hi:[1,0]
	ds_write_b128 v213, v[20:23]
	ds_write_b128 v213, v[24:27] offset:32
	ds_write_b128 v213, v[28:31] offset:64
	ds_write_b128 v213, v[32:35] offset:96
	ds_write_b128 v213, v[4:7] offset:128
	ds_write_b128 v213, v[8:11] offset:160
	ds_write_b128 v213, v[12:15] offset:192
	ds_write_b128 v213, v[16:19] offset:224
	v_add_co_u32_e32 v4, vcc, s80, v48
	ds_read_b128 v[14:17], v214
	ds_read_b128 v[18:21], v214 offset:16
	v_addc_co_u32_e32 v5, vcc, 0, v49, vcc
	v_add_co_u32_e32 v6, vcc, s81, v48
	v_lshl_add_u64 v[12:13], v[46:47], 0, s[34:35]
	s_nop 0
	v_addc_co_u32_e32 v7, vcc, 0, v49, vcc
	global_load_dwordx4 v[8:11], v[4:5], off offset:1024 nt
	s_nop 0
	global_load_dwordx4 v[4:7], v[6:7], off offset:1024 nt
	s_waitcnt vmcnt(3)
	v_lshlrev_b32_e32 v22, 16, v38
	v_and_b32_e32 v23, 0xffff0000, v38
	v_lshlrev_b32_e32 v24, 16, v39
	v_mul_f32_e32 v2, 0xbfb8aa3b, v22
	v_mul_f32_e32 v30, 0xbfb8aa3b, v23
	v_mul_f32_e32 v31, 0xbfb8aa3b, v24
	v_exp_f32_e32 v2, v2
	v_exp_f32_e32 v30, v30
	v_exp_f32_e32 v31, v31
	v_lshlrev_b32_e32 v28, 16, v41
	v_mul_f32_e32 v35, 0xbfb8aa3b, v28
	v_and_b32_e32 v25, 0xffff0000, v39
	v_and_b32_e32 v29, 0xffff0000, v41
	v_exp_f32_e32 v39, v35
	v_add_f32_e32 v2, 1.0, v2
	v_add_f32_e32 v35, 1.0, v30
	v_lshlrev_b32_e32 v26, 16, v40
	v_and_b32_e32 v27, 0xffff0000, v40
	v_mul_f32_e32 v32, 0xbfb8aa3b, v25
	v_mul_f32_e32 v38, 0xbfb8aa3b, v29
	v_add_f32_e32 v40, 1.0, v31
	v_rcp_f32_e32 v30, v2
	v_rcp_f32_e32 v31, v35
	v_mul_f32_e32 v33, 0xbfb8aa3b, v26
	v_mul_f32_e32 v34, 0xbfb8aa3b, v27
	v_exp_f32_e32 v32, v32
	v_exp_f32_e32 v38, v38
	v_exp_f32_e32 v33, v33
	v_exp_f32_e32 v34, v34
	v_pk_mul_f32 v[22:23], v[30:31], v[22:23]
	v_add_f32_e32 v2, 1.0, v39
	v_add_f32_e32 v41, 1.0, v32
	s_waitcnt lgkmcnt(1)
	v_pk_mul_f32 v[14:15], v[22:23], v[14:15]
	v_rcp_f32_e32 v22, v2
	v_add_f32_e32 v2, 1.0, v38
	v_add_f32_e32 v46, 1.0, v33
	v_add_f32_e32 v47, 1.0, v34
	v_rcp_f32_e32 v32, v40
	v_rcp_f32_e32 v33, v41
	v_rcp_f32_e32 v23, v2
	v_rcp_f32_e32 v34, v46
	v_rcp_f32_e32 v35, v47
	v_pk_mul_f32 v[24:25], v[32:33], v[24:25]
	v_pk_mul_f32 v[22:23], v[22:23], v[28:29]
	v_pk_mul_f32 v[16:17], v[24:25], v[16:17]
	v_pk_mul_f32 v[24:25], v[34:35], v[26:27]
	s_waitcnt lgkmcnt(0)
	v_pk_mul_f32 v[20:21], v[22:23], v[20:21]
	s_waitcnt vmcnt(2)
	v_lshlrev_b32_e32 v22, 16, v42
	v_pk_mul_f32 v[18:19], v[24:25], v[18:19]
	v_and_b32_e32 v23, 0xffff0000, v42
	v_mul_f32_e32 v2, 0xbfb8aa3b, v22
	v_cvt_pk_bf16_f32 v14, v14, v15
	v_cvt_pk_bf16_f32 v15, v16, v17
	v_cvt_pk_bf16_f32 v16, v18, v19
	v_exp_f32_e32 v2, v2
	v_mul_f32_e32 v18, 0xbfb8aa3b, v23
	v_cvt_pk_bf16_f32 v17, v20, v21
	v_exp_f32_e32 v20, v18
	v_add_f32_e32 v2, 1.0, v2
	v_rcp_f32_e32 v24, v2
	v_lshl_add_u64 v[18:19], v[12:13], 0, v[36:37]
	v_add_f32_e32 v2, 1.0, v20
	v_rcp_f32_e32 v25, v2
	global_store_dwordx4 v[18:19], v[14:17], off nt
	ds_read_b128 v[14:17], v214 offset:2176
	ds_read_b128 v[18:21], v214 offset:2192
	v_and_b32_e32 v27, 0xffff0000, v44
	v_pk_mul_f32 v[22:23], v[24:25], v[22:23]
	v_lshlrev_b32_e32 v24, 16, v43
	v_and_b32_e32 v25, 0xffff0000, v43
	v_mul_f32_e32 v2, 0xbfb8aa3b, v24
	v_exp_f32_e32 v2, v2
	v_mul_f32_e32 v26, 0xbfb8aa3b, v25
	v_exp_f32_e32 v26, v26
	s_waitcnt lgkmcnt(1)
; #define LAS __attribute__((address_space(3)))
; __device__ __forceinline__ float siluf(float x) { return x * __builtin_amdgcn_rcpf(1.0f + __expf(-x)); }
; __device__ __forceinline__ void unpack8(v4u w, float (&f)[8]) { f[0] = bflo(w.x); f[1] = bfhi(w.x); f[2] = bflo(w.y); f[3] = bfhi(w.y); f[4] = bflo(w.z); f[5] = bfhi(w.z); f[6] = bflo(w.w); f[7] = bfhi(w.w); }
; __device__ __forceinline__ v4u packf8(const float (&f)[8]) { v4u w; w.x = pk2(f[0], f[1]); w.y = pk2(f[2], f[3]); w.z = pk2(f[4], f[5]); w.w = pk2(f[6], f[7]); return w; }
; __device__ __forceinline__ void attn_group(const Params& P, LAS unsigned char* lds, const LAS float* tabh, int s, int h, int c0, int wave, int lane) {
;     ...
; #pragma unroll
;         for (int ps = 0; ps < 4; ++ps) { const int row = 8 * ps + rr;
;             const f32x4 a = *(const LAS f32x4*)(st + row * 272 + pc * 32), b = *(const LAS f32x4*)(st + row * 272 + pc * 32 + 16);
;             float z[8]; unpack8(zb[ps], z);
;             float f[8] = {a[0] * siluf(z[0]), a[1] * siluf(z[1]), a[2] * siluf(z[2]), a[3] * siluf(z[3]), b[0] * siluf(z[4]), b[1] * siluf(z[5]), b[2] * siluf(z[6]), b[3] * siluf(z[7])};
;             *(v4u*)(MIX + (size_t)row * 1024 + 8 * pc) = packf8(f); }
	v_pk_mul_f32 v[14:15], v[22:23], v[14:15]
	v_add_f32_e32 v2, 1.0, v2
	v_rcp_f32_e32 v22, v2
	v_add_f32_e32 v2, 1.0, v26
	v_lshlrev_b32_e32 v26, 16, v44
	v_rcp_f32_e32 v23, v2
	v_mul_f32_e32 v2, 0xbfb8aa3b, v26
	v_exp_f32_e32 v2, v2
	v_mul_f32_e32 v28, 0xbfb8aa3b, v27
	v_exp_f32_e32 v28, v28
	v_pk_mul_f32 v[22:23], v[22:23], v[24:25]
	v_add_f32_e32 v2, 1.0, v2
	v_rcp_f32_e32 v24, v2
	v_add_f32_e32 v2, 1.0, v28
	v_lshlrev_b32_e32 v28, 16, v45
	v_and_b32_e32 v29, 0xffff0000, v45
	v_mul_f32_e32 v25, 0xbfb8aa3b, v28
	v_exp_f32_e32 v30, v25
	v_mul_f32_e32 v25, 0xbfb8aa3b, v29
	v_exp_f32_e32 v31, v25
	v_rcp_f32_e32 v25, v2
	v_add_f32_e32 v2, 1.0, v30
	v_rcp_f32_e32 v30, v2
	v_add_f32_e32 v2, 1.0, v31
	v_rcp_f32_e32 v31, v2
	v_pk_mul_f32 v[16:17], v[22:23], v[16:17]
	v_pk_mul_f32 v[22:23], v[24:25], v[26:27]
	v_cvt_pk_bf16_f32 v14, v14, v15
	s_waitcnt lgkmcnt(0)
	v_pk_mul_f32 v[18:19], v[22:23], v[18:19]
	v_pk_mul_f32 v[22:23], v[30:31], v[28:29]
	v_cvt_pk_bf16_f32 v15, v16, v17
	v_pk_mul_f32 v[20:21], v[22:23], v[20:21]
	s_waitcnt vmcnt(2)
	v_lshlrev_b32_e32 v22, 16, v8
	v_and_b32_e32 v23, 0xffff0000, v8
	v_mul_f32_e32 v8, 0xbfb8aa3b, v22
	v_cvt_pk_bf16_f32 v16, v18, v19
	v_exp_f32_e32 v8, v8
	v_mul_f32_e32 v18, 0xbfb8aa3b, v23
	v_cvt_pk_bf16_f32 v17, v20, v21
	v_exp_f32_e32 v20, v18
	v_lshlrev_b32_e32 v2, 1, v178
	v_lshl_add_u64 v[18:19], v[12:13], 0, v[2:3]
	v_add_f32_e32 v2, 1.0, v8
	v_rcp_f32_e32 v24, v2
	v_add_f32_e32 v2, 1.0, v20
	v_rcp_f32_e32 v25, v2
	v_lshlrev_b32_e32 v8, 16, v9
	v_and_b32_e32 v9, 0xffff0000, v9
	v_mul_f32_e32 v2, 0xbfb8aa3b, v8
	global_store_dwordx4 v[18:19], v[14:17], off nt
	v_pk_mul_f32 v[22:23], v[24:25], v[22:23]
	v_exp_f32_e32 v2, v2
	v_mul_f32_e32 v24, 0xbfb8aa3b, v9
	ds_read_b128 v[14:17], v214 offset:4352
	ds_read_b128 v[18:21], v214 offset:4368
	v_exp_f32_e32 v24, v24
	v_add_f32_e32 v2, 1.0, v2
	v_and_b32_e32 v25, 0xffff0000, v10
	s_waitcnt lgkmcnt(1)
	v_pk_mul_f32 v[14:15], v[22:23], v[14:15]
	v_rcp_f32_e32 v22, v2
	v_add_f32_e32 v2, 1.0, v24
	v_lshlrev_b32_e32 v24, 16, v10
	v_rcp_f32_e32 v23, v2
	v_mul_f32_e32 v2, 0xbfb8aa3b, v24
	v_exp_f32_e32 v2, v2
	v_mul_f32_e32 v10, 0xbfb8aa3b, v25
	v_exp_f32_e32 v26, v10
	v_pk_mul_f32 v[8:9], v[22:23], v[8:9]
	v_lshlrev_b32_e32 v22, 16, v11
	v_add_f32_e32 v2, 1.0, v2
	v_and_b32_e32 v23, 0xffff0000, v11
	v_mul_f32_e32 v11, 0xbfb8aa3b, v22
	v_rcp_f32_e32 v10, v2
	v_add_f32_e32 v2, 1.0, v26
	v_exp_f32_e32 v26, v11
	v_mul_f32_e32 v11, 0xbfb8aa3b, v23
	v_exp_f32_e32 v27, v11
	v_rcp_f32_e32 v11, v2
	v_add_f32_e32 v2, 1.0, v26
	v_rcp_f32_e32 v26, v2
	v_add_f32_e32 v2, 1.0, v27
	v_rcp_f32_e32 v27, v2
	v_pk_mul_f32 v[16:17], v[8:9], v[16:17]
	v_pk_mul_f32 v[8:9], v[10:11], v[24:25]
	s_waitcnt lgkmcnt(0)
	v_pk_mul_f32 v[10:11], v[8:9], v[18:19]
	v_pk_mul_f32 v[8:9], v[26:27], v[22:23]
	v_cvt_pk_bf16_f32 v10, v10, v11
	v_pk_mul_f32 v[18:19], v[8:9], v[20:21]
	v_cvt_pk_bf16_f32 v8, v14, v15
	v_cvt_pk_bf16_f32 v11, v18, v19
	s_waitcnt vmcnt(2)
	v_lshlrev_b32_e32 v18, 16, v4
	v_and_b32_e32 v19, 0xffff0000, v4
	v_mul_f32_e32 v2, 0xbfb8aa3b, v18
	v_exp_f32_e32 v2, v2
	v_mul_f32_e32 v4, 0xbfb8aa3b, v19
	v_exp_f32_e32 v4, v4
	v_cvt_pk_bf16_f32 v9, v16, v17
	v_add_f32_e32 v2, 1.0, v2
	v_rcp_f32_e32 v20, v2
	v_add_f32_e32 v2, 1.0, v4
	v_rcp_f32_e32 v21, v2
	v_lshlrev_b32_e32 v4, 16, v5
	v_lshl_add_u64 v[14:15], v[12:13], 0, v[182:183]
	v_and_b32_e32 v5, 0xffff0000, v5
	v_mul_f32_e32 v2, 0xbfb8aa3b, v4
	global_store_dwordx4 v[14:15], v[8:11], off nt
	v_pk_mul_f32 v[18:19], v[20:21], v[18:19]
	v_exp_f32_e32 v2, v2
	v_mul_f32_e32 v20, 0xbfb8aa3b, v5
	ds_read_b128 v[8:11], v214 offset:6528
	ds_read_b128 v[14:17], v214 offset:6544
	v_exp_f32_e32 v20, v20
	v_add_f32_e32 v2, 1.0, v2
	v_and_b32_e32 v21, 0xffff0000, v6
	s_waitcnt lgkmcnt(1)
	v_pk_mul_f32 v[8:9], v[18:19], v[8:9]
	v_rcp_f32_e32 v18, v2
	v_add_f32_e32 v2, 1.0, v20
	v_lshlrev_b32_e32 v20, 16, v6
	v_rcp_f32_e32 v19, v2
	v_mul_f32_e32 v2, 0xbfb8aa3b, v20
	v_exp_f32_e32 v2, v2
	v_mul_f32_e32 v6, 0xbfb8aa3b, v21
	v_exp_f32_e32 v22, v6
	v_pk_mul_f32 v[4:5], v[18:19], v[4:5]
	v_lshlrev_b32_e32 v18, 16, v7
	v_add_f32_e32 v2, 1.0, v2
	v_and_b32_e32 v19, 0xffff0000, v7
	v_mul_f32_e32 v7, 0xbfb8aa3b, v18
	v_rcp_f32_e32 v6, v2
	v_add_f32_e32 v2, 1.0, v22
	v_exp_f32_e32 v22, v7
	v_mul_f32_e32 v7, 0xbfb8aa3b, v19
	v_exp_f32_e32 v23, v7
	v_rcp_f32_e32 v7, v2
	v_add_f32_e32 v2, 1.0, v22
	v_rcp_f32_e32 v22, v2
	v_add_f32_e32 v2, 1.0, v23
	v_rcp_f32_e32 v23, v2
	v_pk_mul_f32 v[10:11], v[4:5], v[10:11]
	v_pk_mul_f32 v[4:5], v[6:7], v[20:21]
	s_waitcnt lgkmcnt(0)
	v_pk_mul_f32 v[6:7], v[4:5], v[14:15]
	v_pk_mul_f32 v[4:5], v[22:23], v[18:19]
	v_cvt_pk_bf16_f32 v6, v6, v7
	v_pk_mul_f32 v[14:15], v[4:5], v[16:17]
	v_cvt_pk_bf16_f32 v4, v8, v9
	v_cvt_pk_bf16_f32 v5, v10, v11
	v_cvt_pk_bf16_f32 v7, v14, v15
	v_lshl_add_u64 v[8:9], v[12:13], 0, v[184:185]
	global_store_dwordx4 v[8:9], v[4:7], off nt
	s_and_saveexec_b64 s[38:39], s[0:1]
	s_cbranch_execz .LBB0_697
